# stack34 with the per-phase workgroup stagger sleeps shortened (s_sleep 0x55 -> s_sleep 2)
# baseline (speedup 1.0000x reference)
.LBB0_149:
	s_add_i32 s6, s6, -1
	s_cmp_eq_u32 s6, 0
	s_sleep 2
	s_cbranch_scc0 .LBB0_149

.LBB0_224:
	s_add_i32 s2, s2, -1
	s_cmp_eq_u32 s2, 0
	s_sleep 2
	s_cbranch_scc0 .LBB0_224
